# adds: P0 set-up silu(c) with all 32 loads per thread in flight (was 32 serialized load-wait iterations)
# speedup vs baseline: 1.0200x; 1.0107x over previous
.LBB0_17:
	s_load_dwordx16 s[36:51], s[0:1], 0x0
	s_load_dwordx16 s[52:67], s[0:1], 0x40
	v_readlane_b32 s0, v255, 1
	s_lshr_b32 s1, s0, 6
	s_lshl_b32 s0, s2, 3
	s_add_i32 s88, s1, s0
	s_lshl_b32 s76, s74, 3
	s_add_u32 s12, s70, 0x100000
	s_addc_u32 s13, s71, 0
	s_add_u32 s0, s70, 0x7b00000
	v_writelane_b32 v255, s1, 5
	s_addc_u32 s1, s71, 0
	v_writelane_b32 v255, s0, 6
	s_cmp_lt_i32 s72, 1
	v_and_b32_e32 v222, 63, v252
	v_writelane_b32 v255, s1, 7
	s_cselect_b64 s[0:1], -1, 0
	s_cmp_gt_i32 s73, 0
	s_cselect_b64 s[4:5], -1, 0
	s_and_b64 s[0:1], s[0:1], s[4:5]
	s_andn2_b64 vcc, exec, s[0:1]
	s_cbranch_vccnz .LBB0_50
	v_lshlrev_b32_e32 v4, 2, v252
	s_waitcnt lgkmcnt(0)
	v_mov_b32_e32 v5, v4
	global_load_dword v108, v5, s[38:39]
	global_load_dword v109, v5, s[38:39] offset:2048
	v_add_u32_e32 v5, 0x1000, v5
	global_load_dword v110, v5, s[38:39]
	global_load_dword v111, v5, s[38:39] offset:2048
	v_add_u32_e32 v5, 0x1000, v5
	global_load_dword v112, v5, s[38:39]
	global_load_dword v113, v5, s[38:39] offset:2048
	v_add_u32_e32 v5, 0x1000, v5
	global_load_dword v114, v5, s[38:39]
	global_load_dword v115, v5, s[38:39] offset:2048
	v_add_u32_e32 v5, 0x1000, v5
	global_load_dword v116, v5, s[38:39]
	global_load_dword v117, v5, s[38:39] offset:2048
	v_add_u32_e32 v5, 0x1000, v5
	global_load_dword v118, v5, s[38:39]
	global_load_dword v119, v5, s[38:39] offset:2048
	v_add_u32_e32 v5, 0x1000, v5
	global_load_dword v120, v5, s[38:39]
	global_load_dword v121, v5, s[38:39] offset:2048
	v_add_u32_e32 v5, 0x1000, v5
	global_load_dword v122, v5, s[38:39]
	global_load_dword v123, v5, s[38:39] offset:2048
	v_add_u32_e32 v5, 0x1000, v5
	global_load_dword v124, v5, s[38:39]
	global_load_dword v125, v5, s[38:39] offset:2048
	v_add_u32_e32 v5, 0x1000, v5
	global_load_dword v126, v5, s[38:39]
	global_load_dword v127, v5, s[38:39] offset:2048
	v_add_u32_e32 v5, 0x1000, v5
	global_load_dword v128, v5, s[38:39]
	global_load_dword v129, v5, s[38:39] offset:2048
	v_add_u32_e32 v5, 0x1000, v5
	global_load_dword v130, v5, s[38:39]
	global_load_dword v131, v5, s[38:39] offset:2048
	v_add_u32_e32 v5, 0x1000, v5
	global_load_dword v132, v5, s[38:39]
	global_load_dword v133, v5, s[38:39] offset:2048
	v_add_u32_e32 v5, 0x1000, v5
	global_load_dword v134, v5, s[38:39]
	global_load_dword v135, v5, s[38:39] offset:2048
	v_add_u32_e32 v5, 0x1000, v5
	global_load_dword v136, v5, s[38:39]
	global_load_dword v137, v5, s[38:39] offset:2048
	v_add_u32_e32 v5, 0x1000, v5
	global_load_dword v138, v5, s[38:39]
	global_load_dword v139, v5, s[38:39] offset:2048
	s_waitcnt vmcnt(28)
	v_mul_f32_e32 v140, 0xbfb8aa3b, v108
	v_mul_f32_e32 v141, 0xbfb8aa3b, v109
	v_mul_f32_e32 v142, 0xbfb8aa3b, v110
	v_mul_f32_e32 v143, 0xbfb8aa3b, v111
	v_exp_f32_e32 v140, v140
	v_exp_f32_e32 v141, v141
	v_exp_f32_e32 v142, v142
	v_exp_f32_e32 v143, v143
	v_add_f32_e32 v140, 1.0, v140
	v_add_f32_e32 v141, 1.0, v141
	v_add_f32_e32 v142, 1.0, v142
	v_add_f32_e32 v143, 1.0, v143
	v_rcp_f32_e32 v140, v140
	v_rcp_f32_e32 v141, v141
	v_rcp_f32_e32 v142, v142
	v_rcp_f32_e32 v143, v143
	v_mul_f32_e32 v140, v108, v140
	v_mul_f32_e32 v141, v109, v141
	v_mul_f32_e32 v142, v110, v142
	v_mul_f32_e32 v143, v111, v143
	ds_write_b32 v4, v140
	ds_write_b32 v4, v141 offset:2048
	ds_write_b32 v4, v142 offset:4096
	ds_write_b32 v4, v143 offset:6144
	s_waitcnt vmcnt(24)
	v_mul_f32_e32 v140, 0xbfb8aa3b, v112
	v_mul_f32_e32 v141, 0xbfb8aa3b, v113
	v_mul_f32_e32 v142, 0xbfb8aa3b, v114
	v_mul_f32_e32 v143, 0xbfb8aa3b, v115
	v_exp_f32_e32 v140, v140
	v_exp_f32_e32 v141, v141
	v_exp_f32_e32 v142, v142
	v_exp_f32_e32 v143, v143
	v_add_f32_e32 v140, 1.0, v140
	v_add_f32_e32 v141, 1.0, v141
	v_add_f32_e32 v142, 1.0, v142
	v_add_f32_e32 v143, 1.0, v143
	v_rcp_f32_e32 v140, v140
	v_rcp_f32_e32 v141, v141
	v_rcp_f32_e32 v142, v142
	v_rcp_f32_e32 v143, v143
	v_mul_f32_e32 v140, v112, v140
	v_mul_f32_e32 v141, v113, v141
	v_mul_f32_e32 v142, v114, v142
	v_mul_f32_e32 v143, v115, v143
	ds_write_b32 v4, v140 offset:8192
	ds_write_b32 v4, v141 offset:10240
	ds_write_b32 v4, v142 offset:12288
	ds_write_b32 v4, v143 offset:14336
	s_waitcnt vmcnt(20)
	v_mul_f32_e32 v140, 0xbfb8aa3b, v116
	v_mul_f32_e32 v141, 0xbfb8aa3b, v117
	v_mul_f32_e32 v142, 0xbfb8aa3b, v118
	v_mul_f32_e32 v143, 0xbfb8aa3b, v119
	v_exp_f32_e32 v140, v140
	v_exp_f32_e32 v141, v141
	v_exp_f32_e32 v142, v142
	v_exp_f32_e32 v143, v143
	v_add_f32_e32 v140, 1.0, v140
	v_add_f32_e32 v141, 1.0, v141
	v_add_f32_e32 v142, 1.0, v142
	v_add_f32_e32 v143, 1.0, v143
	v_rcp_f32_e32 v140, v140
	v_rcp_f32_e32 v141, v141
	v_rcp_f32_e32 v142, v142
	v_rcp_f32_e32 v143, v143
	v_mul_f32_e32 v140, v116, v140
	v_mul_f32_e32 v141, v117, v141
	v_mul_f32_e32 v142, v118, v142
	v_mul_f32_e32 v143, v119, v143
	ds_write_b32 v4, v140 offset:16384
	ds_write_b32 v4, v141 offset:18432
	ds_write_b32 v4, v142 offset:20480
	ds_write_b32 v4, v143 offset:22528
	s_waitcnt vmcnt(16)
	v_mul_f32_e32 v140, 0xbfb8aa3b, v120
	v_mul_f32_e32 v141, 0xbfb8aa3b, v121
	v_mul_f32_e32 v142, 0xbfb8aa3b, v122
	v_mul_f32_e32 v143, 0xbfb8aa3b, v123
	v_exp_f32_e32 v140, v140
	v_exp_f32_e32 v141, v141
	v_exp_f32_e32 v142, v142
	v_exp_f32_e32 v143, v143
	v_add_f32_e32 v140, 1.0, v140
	v_add_f32_e32 v141, 1.0, v141
	v_add_f32_e32 v142, 1.0, v142
	v_add_f32_e32 v143, 1.0, v143
	v_rcp_f32_e32 v140, v140
	v_rcp_f32_e32 v141, v141
	v_rcp_f32_e32 v142, v142
	v_rcp_f32_e32 v143, v143
	v_mul_f32_e32 v140, v120, v140
	v_mul_f32_e32 v141, v121, v141
	v_mul_f32_e32 v142, v122, v142
	v_mul_f32_e32 v143, v123, v143
	ds_write_b32 v4, v140 offset:24576
	ds_write_b32 v4, v141 offset:26624
	ds_write_b32 v4, v142 offset:28672
	ds_write_b32 v4, v143 offset:30720
	s_waitcnt vmcnt(12)
	v_mul_f32_e32 v140, 0xbfb8aa3b, v124
	v_mul_f32_e32 v141, 0xbfb8aa3b, v125
	v_mul_f32_e32 v142, 0xbfb8aa3b, v126
	v_mul_f32_e32 v143, 0xbfb8aa3b, v127
	v_exp_f32_e32 v140, v140
	v_exp_f32_e32 v141, v141
	v_exp_f32_e32 v142, v142
	v_exp_f32_e32 v143, v143
	v_add_f32_e32 v140, 1.0, v140
	v_add_f32_e32 v141, 1.0, v141
	v_add_f32_e32 v142, 1.0, v142
	v_add_f32_e32 v143, 1.0, v143
	v_rcp_f32_e32 v140, v140
	v_rcp_f32_e32 v141, v141
	v_rcp_f32_e32 v142, v142
	v_rcp_f32_e32 v143, v143
	v_mul_f32_e32 v140, v124, v140
	v_mul_f32_e32 v141, v125, v141
	v_mul_f32_e32 v142, v126, v142
	v_mul_f32_e32 v143, v127, v143
	ds_write_b32 v4, v140 offset:32768
	ds_write_b32 v4, v141 offset:34816
	ds_write_b32 v4, v142 offset:36864
	ds_write_b32 v4, v143 offset:38912
	s_waitcnt vmcnt(8)
	v_mul_f32_e32 v140, 0xbfb8aa3b, v128
	v_mul_f32_e32 v141, 0xbfb8aa3b, v129
	v_mul_f32_e32 v142, 0xbfb8aa3b, v130
	v_mul_f32_e32 v143, 0xbfb8aa3b, v131
	v_exp_f32_e32 v140, v140
	v_exp_f32_e32 v141, v141
	v_exp_f32_e32 v142, v142
	v_exp_f32_e32 v143, v143
	v_add_f32_e32 v140, 1.0, v140
	v_add_f32_e32 v141, 1.0, v141
	v_add_f32_e32 v142, 1.0, v142
	v_add_f32_e32 v143, 1.0, v143
	v_rcp_f32_e32 v140, v140
	v_rcp_f32_e32 v141, v141
	v_rcp_f32_e32 v142, v142
	v_rcp_f32_e32 v143, v143
	v_mul_f32_e32 v140, v128, v140
	v_mul_f32_e32 v141, v129, v141
	v_mul_f32_e32 v142, v130, v142
	v_mul_f32_e32 v143, v131, v143
	ds_write_b32 v4, v140 offset:40960
	ds_write_b32 v4, v141 offset:43008
	ds_write_b32 v4, v142 offset:45056
	ds_write_b32 v4, v143 offset:47104
	s_waitcnt vmcnt(4)
	v_mul_f32_e32 v140, 0xbfb8aa3b, v132
	v_mul_f32_e32 v141, 0xbfb8aa3b, v133
	v_mul_f32_e32 v142, 0xbfb8aa3b, v134
	v_mul_f32_e32 v143, 0xbfb8aa3b, v135
	v_exp_f32_e32 v140, v140
	v_exp_f32_e32 v141, v141
	v_exp_f32_e32 v142, v142
	v_exp_f32_e32 v143, v143
	v_add_f32_e32 v140, 1.0, v140
	v_add_f32_e32 v141, 1.0, v141
	v_add_f32_e32 v142, 1.0, v142
	v_add_f32_e32 v143, 1.0, v143
	v_rcp_f32_e32 v140, v140
	v_rcp_f32_e32 v141, v141
	v_rcp_f32_e32 v142, v142
	v_rcp_f32_e32 v143, v143
	v_mul_f32_e32 v140, v132, v140
	v_mul_f32_e32 v141, v133, v141
	v_mul_f32_e32 v142, v134, v142
	v_mul_f32_e32 v143, v135, v143
	ds_write_b32 v4, v140 offset:49152
	ds_write_b32 v4, v141 offset:51200
	ds_write_b32 v4, v142 offset:53248
	ds_write_b32 v4, v143 offset:55296
	s_waitcnt vmcnt(0)
	v_mul_f32_e32 v140, 0xbfb8aa3b, v136
	v_mul_f32_e32 v141, 0xbfb8aa3b, v137
	v_mul_f32_e32 v142, 0xbfb8aa3b, v138
	v_mul_f32_e32 v143, 0xbfb8aa3b, v139
	v_exp_f32_e32 v140, v140
	v_exp_f32_e32 v141, v141
	v_exp_f32_e32 v142, v142
	v_exp_f32_e32 v143, v143
	v_add_f32_e32 v140, 1.0, v140
	v_add_f32_e32 v141, 1.0, v141
	v_add_f32_e32 v142, 1.0, v142
	v_add_f32_e32 v143, 1.0, v143
	v_rcp_f32_e32 v140, v140
	v_rcp_f32_e32 v141, v141
	v_rcp_f32_e32 v142, v142
	v_rcp_f32_e32 v143, v143
	v_mul_f32_e32 v140, v136, v140
	v_mul_f32_e32 v141, v137, v141
	v_mul_f32_e32 v142, v138, v142
	v_mul_f32_e32 v143, v139, v143
	ds_write_b32 v4, v140 offset:57344
	ds_write_b32 v4, v141 offset:59392
	ds_write_b32 v4, v142 offset:61440
	ds_write_b32 v4, v143 offset:63488
	s_cmp_gt_i32 s88, 0xa7ff
	s_waitcnt lgkmcnt(0)
	s_barrier
	s_cbranch_scc1 .LBB0_50
	v_lshlrev_b32_e32 v0, 3, v222
	v_mov_b32_e32 v1, 0
	s_add_u32 s8, s70, 0x1d000000
	v_readlane_b32 s3, v255, 5
	v_lshl_add_u64 v[2:3], s[52:53], 0, v[0:1]
	v_lshlrev_b32_e32 v0, 2, v222
	v_lshlrev_b32_e32 v8, 3, v252
	s_addc_u32 s9, s71, 0
	s_mul_i32 s4, s3, 0x2200
	s_add_i32 s10, 0, 0x10000
	v_lshl_add_u64 v[4:5], s[70:71], 0, v[0:1]
	s_mov_b64 s[6:7], 0x22200000
	v_lshrrev_b32_e32 v33, 3, v222
	v_and_b32_e32 v12, 56, v8
	s_add_i32 s3, s10, s4
	v_lshl_add_u64 v[4:5], v[4:5], 0, s[6:7]
	v_lshrrev_b32_e32 v16, 5, v222
	v_mul_u32_u24_e32 v10, 0x84, v12
	v_readlane_b32 s6, v255, 6
	v_lshlrev_b32_e32 v11, 2, v33
	v_and_b32_e32 v0, 31, v252
	v_mov_b32_e32 v13, v1
	v_readlane_b32 s7, v255, 7
	v_add3_u32 v34, s3, v10, v11
	v_and_b32_e32 v10, 7, v252
	v_mul_u32_u24_e32 v14, 0x84, v16
	v_lshlrev_b32_e32 v0, 2, v0
	v_lshl_add_u64 v[8:9], s[6:7], 0, v[12:13]
	v_lshlrev_b32_e32 v10, 4, v10
	v_mov_b32_e32 v11, v1
	v_lshl_add_u64 v[12:13], s[70:71], 0, v[12:13]
	s_mov_b64 s[6:7], 0x22300000
	v_or_b32_e32 v14, s4, v14
	s_mov_b32 s5, 0
	v_lshlrev_b32_e32 v32, 1, v222
	v_lshl_add_u64 v[6:7], s[66:67], 0, v[0:1]
	v_or_b32_e32 v35, 8, v33
	v_or_b32_e32 v36, 16, v33
	v_or_b32_e32 v37, 24, v33
	v_lshl_add_u64 v[10:11], s[12:13], 0, v[10:11]
	v_lshl_add_u64 v[12:13], v[12:13], 0, s[6:7]
	v_lshlrev_b32_e32 v38, 12, v16
	s_add_i32 s3, s88, 0xffff8000
	v_add3_u32 v39, v14, v0, s10
	v_lshl_add_u64 v[14:15], s[46:47], 0, v[0:1]
	v_mul_u32_u24_e32 v40, 0x3ca0, v16
	v_or_b32_e32 v41, 14, v16
	v_or_b32_e32 v42, 12, v16
	v_or_b32_e32 v43, 2, v16
	v_or_b32_e32 v44, 10, v16
	v_or_b32_e32 v45, 8, v16
	v_or_b32_e32 v46, 6, v16
	v_or_b32_e32 v47, 4, v16
	s_mov_b32 s14, 0xc000
	s_mov_b32 s15, 0xc3e00000
	s_mov_b32 s16, 0x30000
	s_mov_b32 s17, 0x18000
	s_mov_b32 s18, 0x24000
	s_mov_b32 s19, 0x3c000
	s_mov_b32 s20, 0x48000
	s_mov_b32 s21, 0x54000
	v_mov_b32_e32 v48, 0x43e00000
	v_mov_b32_e32 v49, 0x30000
	s_mov_b32 s22, s88
	s_branch .LBB0_23
